# DeltaNet prep S5 output stores: SGPR base + 32-bit VGPR offset addressing (drops 64 VALU address instructions per unit)
# baseline (speedup 1.0000x reference)
.Lsv_b14:
	v_fmac_f32_e32 v108, v212, v106
	v_fmac_f32_e32 v109, v220, v106
	v_fmac_f32_e32 v110, v228, v106
	v_fmac_f32_e32 v111, v236, v106
	s_waitcnt lgkmcnt(0)
	ds_read_b128 v[176:179], v128 offset:15360
	ds_read_b128 v[180:183], v128 offset:15376
	ds_read_b128 v[184:187], v128 offset:15616
	ds_read_b128 v[188:191], v128 offset:15632
	ds_read_b128 v[192:195], v128 offset:15872
	ds_read_b128 v[196:199], v128 offset:15888
	ds_read_b128 v[200:203], v128 offset:16128
	ds_read_b128 v[238:241], v128 offset:16144
	ds_read_b32 v146, v129 offset:15772
	ds_read_b32 v147, v129 offset:16028
	ds_read_b32 v148, v129 offset:16060
	ds_read_b32 v149, v129 offset:16284
	ds_read_b32 v150, v129 offset:16316
	ds_read_b32 v151, v129 offset:16348
	v_add_f32_dpp v108, v108, v108 quad_perm:[1,0,3,2] row_mask:0xf bank_mask:0xf bound_ctrl:1
	v_add_f32_dpp v109, v109, v109 quad_perm:[1,0,3,2] row_mask:0xf bank_mask:0xf bound_ctrl:1
	v_cmp_eq_u32_e32 vcc, 60, v0
	v_add_f32_dpp v110, v110, v110 quad_perm:[1,0,3,2] row_mask:0xf bank_mask:0xf bound_ctrl:1
	v_add_f32_dpp v111, v111, v111 quad_perm:[1,0,3,2] row_mask:0xf bank_mask:0xf bound_ctrl:1
	v_cndmask_b32_e64 v120, 0, 1.0, vcc
	v_cmp_eq_u32_e32 vcc, 61, v0
	v_add_f32_dpp v108, v108, v108 quad_perm:[2,3,0,1] row_mask:0xf bank_mask:0xf bound_ctrl:1
	v_add_f32_dpp v109, v109, v109 quad_perm:[2,3,0,1] row_mask:0xf bank_mask:0xf bound_ctrl:1
	v_cndmask_b32_e64 v121, 0, 1.0, vcc
	v_cmp_eq_u32_e32 vcc, 62, v0
	v_add_f32_dpp v110, v110, v110 quad_perm:[2,3,0,1] row_mask:0xf bank_mask:0xf bound_ctrl:1
	v_add_f32_dpp v111, v111, v111 quad_perm:[2,3,0,1] row_mask:0xf bank_mask:0xf bound_ctrl:1
	v_cndmask_b32_e64 v122, 0, 1.0, vcc
	v_cmp_eq_u32_e32 vcc, 63, v0
	v_add_f32_dpp v108, v108, v108 row_half_mirror row_mask:0xf bank_mask:0xf bound_ctrl:1
	v_add_f32_dpp v109, v109, v109 row_half_mirror row_mask:0xf bank_mask:0xf bound_ctrl:1
	v_cndmask_b32_e64 v123, 0, 1.0, vcc
	v_add_f32_dpp v110, v110, v110 row_half_mirror row_mask:0xf bank_mask:0xf bound_ctrl:1
	v_add_f32_dpp v111, v111, v111 row_half_mirror row_mask:0xf bank_mask:0xf bound_ctrl:1
	v_sub_f32_e32 v124, v116, v108
	v_sub_f32_e32 v125, v117, v109
	v_sub_f32_e32 v126, v118, v110
	v_sub_f32_e32 v127, v119, v111
	v_fma_f32 v125, -v130, v124, v125
	v_fma_f32 v126, -v131, v124, v126
	v_fma_f32 v127, -v133, v124, v127
	s_waitcnt lgkmcnt(13)
	v_mul_f32_e32 v112, v176, v100
	s_waitcnt lgkmcnt(11)
	v_mul_f32_e32 v113, v184, v100
	v_fma_f32 v126, -v132, v125, v126
	v_fma_f32 v127, -v134, v125, v127
	s_waitcnt lgkmcnt(9)
	v_mul_f32_e32 v114, v192, v100
	s_waitcnt lgkmcnt(7)
	v_mul_f32_e32 v115, v200, v100
	v_fma_f32 v127, -v135, v126, v127
	v_fmac_f32_e32 v112, v177, v101
	v_fmac_f32_e32 v113, v185, v101
	v_cndmask_b32_e64 v107, v107, v124, s[6:7]
	v_fmac_f32_e32 v114, v193, v101
	v_cndmask_b32_e64 v107, v107, v125, s[8:9]
	v_fmac_f32_e32 v115, v201, v101
	v_cndmask_b32_e64 v107, v107, v126, s[10:11]
	v_fmac_f32_e32 v112, v178, v102
	v_cndmask_b32_e64 v107, v107, v127, s[12:13]
	v_fmac_f32_e32 v113, v186, v102
	v_fmac_f32_e32 v114, v194, v102
	v_fmac_f32_e32 v115, v202, v102
	v_fmac_f32_e32 v112, v179, v103
	v_fmac_f32_e32 v113, v187, v103
	v_fmac_f32_e32 v114, v195, v103
	v_fmac_f32_e32 v115, v203, v103
	v_fmac_f32_e32 v112, v180, v104
	v_fmac_f32_e32 v113, v188, v104
	v_fmac_f32_e32 v114, v196, v104
	s_waitcnt lgkmcnt(6)
	v_fmac_f32_e32 v115, v238, v104
	v_fmac_f32_e32 v112, v181, v105
	v_fmac_f32_e32 v113, v189, v105
	v_fmac_f32_e32 v114, v197, v105
	v_fmac_f32_e32 v115, v239, v105
	v_fmac_f32_e32 v112, v182, v106
	v_fmac_f32_e32 v113, v190, v106
	v_fmac_f32_e32 v114, v198, v106
	v_fmac_f32_e32 v115, v240, v106
	v_fmac_f32_e32 v112, v183, v107
	v_fmac_f32_e32 v113, v191, v107
	v_fmac_f32_e32 v114, v199, v107
	v_fmac_f32_e32 v115, v241, v107
	v_add_f32_dpp v112, v112, v112 quad_perm:[1,0,3,2] row_mask:0xf bank_mask:0xf bound_ctrl:1
	v_add_f32_dpp v113, v113, v113 quad_perm:[1,0,3,2] row_mask:0xf bank_mask:0xf bound_ctrl:1
	v_add_f32_dpp v114, v114, v114 quad_perm:[1,0,3,2] row_mask:0xf bank_mask:0xf bound_ctrl:1
	v_add_f32_dpp v115, v115, v115 quad_perm:[1,0,3,2] row_mask:0xf bank_mask:0xf bound_ctrl:1
	v_add_f32_dpp v112, v112, v112 quad_perm:[2,3,0,1] row_mask:0xf bank_mask:0xf bound_ctrl:1
	v_add_f32_dpp v113, v113, v113 quad_perm:[2,3,0,1] row_mask:0xf bank_mask:0xf bound_ctrl:1
	v_add_f32_dpp v114, v114, v114 quad_perm:[2,3,0,1] row_mask:0xf bank_mask:0xf bound_ctrl:1
	v_add_f32_dpp v115, v115, v115 quad_perm:[2,3,0,1] row_mask:0xf bank_mask:0xf bound_ctrl:1
	v_add_f32_dpp v112, v112, v112 row_half_mirror row_mask:0xf bank_mask:0xf bound_ctrl:1
	v_add_f32_dpp v113, v113, v113 row_half_mirror row_mask:0xf bank_mask:0xf bound_ctrl:1
	v_add_f32_dpp v114, v114, v114 row_half_mirror row_mask:0xf bank_mask:0xf bound_ctrl:1
	v_add_f32_dpp v115, v115, v115 row_half_mirror row_mask:0xf bank_mask:0xf bound_ctrl:1
	v_sub_f32_e32 v124, v120, v112
	v_sub_f32_e32 v125, v121, v113
	v_sub_f32_e32 v126, v122, v114
	v_sub_f32_e32 v127, v123, v115
	s_waitcnt lgkmcnt(5)
	v_fma_f32 v125, -v146, v124, v125
	s_waitcnt lgkmcnt(4)
	v_fma_f32 v126, -v147, v124, v126
	s_waitcnt lgkmcnt(2)
	v_fma_f32 v127, -v149, v124, v127
	v_fma_f32 v126, -v148, v125, v126
	s_waitcnt lgkmcnt(1)
	v_fma_f32 v127, -v150, v125, v127
	s_waitcnt lgkmcnt(0)
	v_fma_f32 v127, -v151, v126, v127
	v_cndmask_b32_e64 v107, v107, v124, s[14:15]
	v_cndmask_b32_e64 v107, v107, v125, s[16:17]
	v_cndmask_b32_e64 v107, v107, v126, s[18:19]
	v_cndmask_b32_e64 v107, v107, v127, s[20:21]
	v_lshl_add_u32 v152, v0, 2, 0
	v_add_u32_e32 v153, 0x15c00, v152
	v_add_u32_e32 v154, 0x15e00, v152
	v_add_u32_e32 v155, 0x15f00, v152
	ds_read_b32 v153, v153
	ds_read_b32 v154, v154
	ds_read_b32 v155, v155
	v_mul_u32_u24_e32 v156, 0x48, v2
	v_add_lshl_u32 v156, v0, v156, 1
	v_readlane_b32 s6, v244, 27
	v_readlane_b32 s7, v244, 32
	s_lshl_b64 s[8:9], s[36:37], 14
	s_mov_b32 s36, s2
	s_nop 1
	v_add_u32_e32 v157, s6, v156
	v_add_u32_e32 v156, s7, v156
	s_waitcnt lgkmcnt(0)
	v_mul_f32_e32 v154, v153, v154
	v_mul_f32_e32 v154, v154, v155
	v_mul_f32_e32 v158, v100, v153
	v_mul_f32_e32 v159, v100, v154
	v_cvt_pk_bf16_f32 v158, v158, v158
	v_cvt_pk_bf16_f32 v159, v159, v159
	ds_write_b16 v157, v158 offset:0
	ds_write_b16 v156, v159 offset:0
	v_mul_f32_e32 v158, v101, v153
	v_mul_f32_e32 v159, v101, v154
	v_cvt_pk_bf16_f32 v158, v158, v158
	v_cvt_pk_bf16_f32 v159, v159, v159
	ds_write_b16 v157, v158 offset:1152
	ds_write_b16 v156, v159 offset:1152
	v_mul_f32_e32 v158, v102, v153
	v_mul_f32_e32 v159, v102, v154
	v_cvt_pk_bf16_f32 v158, v158, v158
	v_cvt_pk_bf16_f32 v159, v159, v159
	ds_write_b16 v157, v158 offset:2304
	ds_write_b16 v156, v159 offset:2304
	v_mul_f32_e32 v158, v103, v153
	v_mul_f32_e32 v159, v103, v154
	v_cvt_pk_bf16_f32 v158, v158, v158
	v_cvt_pk_bf16_f32 v159, v159, v159
	ds_write_b16 v157, v158 offset:3456
	ds_write_b16 v156, v159 offset:3456
	v_mul_f32_e32 v158, v104, v153
	v_mul_f32_e32 v159, v104, v154
	v_cvt_pk_bf16_f32 v158, v158, v158
	v_cvt_pk_bf16_f32 v159, v159, v159
	ds_write_b16 v157, v158 offset:4608
	ds_write_b16 v156, v159 offset:4608
	v_mul_f32_e32 v158, v105, v153
	v_mul_f32_e32 v159, v105, v154
	v_cvt_pk_bf16_f32 v158, v158, v158
	v_cvt_pk_bf16_f32 v159, v159, v159
	ds_write_b16 v157, v158 offset:5760
	ds_write_b16 v156, v159 offset:5760
	v_mul_f32_e32 v158, v106, v153
	v_mul_f32_e32 v159, v106, v154
	v_cvt_pk_bf16_f32 v158, v158, v158
	v_cvt_pk_bf16_f32 v159, v159, v159
	ds_write_b16 v157, v158 offset:6912
	ds_write_b16 v156, v159 offset:6912
	v_mul_f32_e32 v158, v107, v153
	v_mul_f32_e32 v159, v107, v154
	v_cvt_pk_bf16_f32 v158, v158, v158
	v_cvt_pk_bf16_f32 v159, v159, v159
	ds_write_b16 v157, v158 offset:8064
	ds_write_b16 v156, v159 offset:8064
	v_mul_u32_u24_e32 v0, 0x48, v46
	v_lshlrev_b32_e32 v0, 1, v0
	v_add3_u32 v84, s6, v0, v48
	s_waitcnt lgkmcnt(0)
	s_barrier
	ds_read_b128 v[2:5], v84
	v_lshl_or_b32 v46, v43, 4, v46
	s_movk_i32 s6, 0x90
	v_mul_lo_u32 v6, v46, s6
	v_add3_u32 v56, 0, v6, v48
	ds_read_b128 v[6:9], v56 offset:35840
	ds_read_b128 v[10:13], v84 offset:64
	ds_read_b128 v[14:17], v56 offset:35904
	s_waitcnt lgkmcnt(2)
	v_mfma_f32_16x16x32_bf16 v[2:5], v[2:5], v[6:9], 0
	v_add3_u32 v0, s7, v0, v48
	ds_read_b128 v[42:45], v0
	ds_read_b128 v[48:51], v56 offset:17408
	ds_read_b128 v[52:55], v0 offset:64
	s_add_u32 s6, s22, s8
	s_waitcnt lgkmcnt(3)
	v_mfma_f32_16x16x32_bf16 v[2:5], v[10:13], v[14:17], v[2:5]
	ds_read_b128 v[10:13], v56 offset:17472
	s_addc_u32 s7, s23, s9
	v_lshl_add_u32 v46, v47, 7, v46
	v_lshlrev_b32_e32 v100, 1, v46
	v_add_u32_e32 v101, 0x1000, v100
	v_add_u32_e32 v102, 0x2000, v100
	v_add_u32_e32 v103, 0x3000, v100
	s_waitcnt lgkmcnt(2)
	v_mfma_f32_16x16x32_bf16 v[42:45], v[42:45], v[48:51], 0
	ds_read_b128 v[60:63], v0 offset:2304
	ds_read_b128 v[64:67], v0 offset:2368
	s_add_u32 s8, s59, s8
	s_waitcnt lgkmcnt(2)
	v_mfma_f32_16x16x32_bf16 v[42:45], v[52:55], v[10:13], v[42:45]
	s_addc_u32 s9, s64, s9
	v_cvt_pk_bf16_f32 v2, v2, s0
	ds_read_b128 v[52:55], v84 offset:2304
	global_store_short v100, v2, s[8:9]
	s_nop 0
	s_nop 3
	v_cvt_pk_bf16_f32 v2, v42, s0
	global_store_short v100, v2, s[6:7]
	v_cvt_pk_bf16_f32 v2, v3, s0
	global_store_short v100, v2, s[8:9] offset:256
	v_cvt_pk_bf16_f32 v2, v43, s0
	ds_read_b128 v[56:59], v84 offset:2368
	global_store_short v100, v2, s[6:7] offset:256
	v_cvt_pk_bf16_f32 v2, v4, s0
	global_store_short v100, v2, s[8:9] offset:512
	v_cvt_pk_bf16_f32 v2, v44, s0
	global_store_short v100, v2, s[6:7] offset:512
	v_cvt_pk_bf16_f32 v42, v5, s0
	s_waitcnt lgkmcnt(3)
	v_mfma_f32_16x16x32_bf16 v[2:5], v[60:63], v[48:51], 0
	global_store_short v100, v42, s[8:9] offset:768
	v_cvt_pk_bf16_f32 v42, v45, s0
	global_store_short v100, v42, s[6:7] offset:768
	s_waitcnt lgkmcnt(1)
	v_mfma_f32_16x16x32_bf16 v[52:55], v[52:55], v[6:9], 0
	v_mfma_f32_16x16x32_bf16 v[2:5], v[64:67], v[10:13], v[2:5]
	ds_read_b128 v[60:63], v0 offset:4672
	s_waitcnt lgkmcnt(1)
	v_mfma_f32_16x16x32_bf16 v[52:55], v[56:59], v[14:17], v[52:55]
	ds_read_b128 v[56:59], v84 offset:4672
	s_nop 1
	s_nop 3
	v_cvt_pk_bf16_f32 v2, v2, s0
	global_store_short v101, v2, s[6:7]
	s_nop 0
	v_cvt_pk_bf16_f32 v47, v52, s0
	global_store_short v101, v47, s[8:9]
	v_cvt_pk_bf16_f32 v2, v53, s0
	global_store_short v101, v2, s[8:9] offset:256
	v_cvt_pk_bf16_f32 v44, v3, s0
	global_store_short v101, v44, s[6:7] offset:256
	ds_read_b128 v[42:45], v84 offset:4608
	v_cvt_pk_bf16_f32 v47, v54, s0
	v_cvt_pk_bf16_f32 v4, v4, s0
	global_store_short v101, v47, s[8:9] offset:512
	global_store_short v101, v4, s[6:7] offset:512
	v_cvt_pk_bf16_f32 v4, v55, s0
	ds_read_b128 v[52:55], v0 offset:4608
	s_waitcnt lgkmcnt(1)
	v_mfma_f32_16x16x32_bf16 v[42:45], v[42:45], v[6:9], 0
	s_waitcnt lgkmcnt(0)
	v_mfma_f32_16x16x32_bf16 v[52:55], v[52:55], v[48:51], 0
	s_and_b64 vcc, exec, s[38:39]
	v_mfma_f32_16x16x32_bf16 v[42:45], v[56:59], v[14:17], v[42:45]
	global_store_short v101, v4, s[8:9] offset:768
	v_cvt_pk_bf16_f32 v4, v5, s0
	global_store_short v101, v4, s[6:7] offset:768
	v_mfma_f32_16x16x32_bf16 v[2:5], v[60:63], v[10:13], v[52:55]
	s_nop 1
	s_nop 2
	v_cvt_pk_bf16_f32 v42, v42, s0
	v_cvt_pk_bf16_f32 v44, v44, s0
	ds_read_b128 v[56:59], v84 offset:6976
	global_store_short v102, v42, s[8:9]
	v_cvt_pk_bf16_f32 v2, v2, s0
	global_store_short v102, v2, s[6:7]
	v_cvt_pk_bf16_f32 v2, v43, s0
	global_store_short v102, v2, s[8:9] offset:256
	v_cvt_pk_bf16_f32 v47, v3, s0
	ds_read_b128 v[52:55], v84 offset:6912
	global_store_short v102, v47, s[6:7] offset:256
	v_cvt_pk_bf16_f32 v4, v4, s0
	global_store_short v102, v44, s[8:9] offset:512
	global_store_short v102, v4, s[6:7] offset:512
	v_cvt_pk_bf16_f32 v4, v45, s0
	ds_read_b128 v[42:45], v0 offset:6912
	s_waitcnt lgkmcnt(1)
	v_mfma_f32_16x16x32_bf16 v[6:9], v[52:55], v[6:9], 0
	ds_read_b128 v[52:55], v0 offset:6976
	v_mfma_f32_16x16x32_bf16 v[6:9], v[56:59], v[14:17], v[6:9]
	global_store_short v102, v4, s[8:9] offset:768
	v_cvt_pk_bf16_f32 v0, v5, s0
	s_waitcnt lgkmcnt(1)
	v_mfma_f32_16x16x32_bf16 v[14:17], v[42:45], v[48:51], 0
	global_store_short v102, v0, s[6:7] offset:768
	s_nop 0
	s_nop 3
	v_cvt_pk_bf16_f32 v0, v6, s0
	s_waitcnt lgkmcnt(0)
	v_mfma_f32_16x16x32_bf16 v[2:5], v[52:55], v[10:13], v[14:17]
	global_store_short v103, v0, s[8:9]
	s_nop 2
	s_nop 4
	v_cvt_pk_bf16_f32 v0, v2, s0
	global_store_short v103, v0, s[6:7]
	v_cvt_pk_bf16_f32 v0, v7, s0
	global_store_short v103, v0, s[8:9] offset:256
	v_cvt_pk_bf16_f32 v0, v3, s0
	global_store_short v103, v0, s[6:7] offset:256
	v_cvt_pk_bf16_f32 v0, v8, s0
	global_store_short v103, v0, s[8:9] offset:512
	v_cvt_pk_bf16_f32 v0, v4, s0
	global_store_short v103, v0, s[6:7] offset:512
	v_cvt_pk_bf16_f32 v0, v9, s0
	global_store_short v103, v0, s[8:9] offset:768
	v_cvt_pk_bf16_f32 v0, v5, s0
	global_store_short v103, v0, s[6:7] offset:768
	s_cbranch_vccnz .LBB0_601
